# P4 k_nope pre-normalisation pass software-pipelined: 16 rows in flight per wave, one counted vmcnt per row
# baseline (speedup 1.0000x reference)
.Lkn_loop:
	s_mul_i32 s14, s17, 15
	s_add_u32 s14, s14, s16
	s_cmp_ge_u32 s14, 0x8000
	s_cbranch_scc1 .Lkn_slow
	s_mov_b32 s14, s16
	v_mov_b32_e32 v184, s14
	v_lshl_add_u32 v184, v184, 11, v105
	global_load_dwordx4 v[120:123], v184, s[12:13]
	s_add_u32 s14, s14, s17
	v_mov_b32_e32 v185, s14
	v_lshl_add_u32 v185, v185, 11, v105
	global_load_dwordx4 v[124:127], v185, s[12:13]
	s_add_u32 s14, s14, s17
	v_mov_b32_e32 v186, s14
	v_lshl_add_u32 v186, v186, 11, v105
	global_load_dwordx4 v[128:131], v186, s[12:13]
	s_add_u32 s14, s14, s17
	v_mov_b32_e32 v187, s14
	v_lshl_add_u32 v187, v187, 11, v105
	global_load_dwordx4 v[132:135], v187, s[12:13]
	s_add_u32 s14, s14, s17
	v_mov_b32_e32 v188, s14
	v_lshl_add_u32 v188, v188, 11, v105
	global_load_dwordx4 v[136:139], v188, s[12:13]
	s_add_u32 s14, s14, s17
	v_mov_b32_e32 v189, s14
	v_lshl_add_u32 v189, v189, 11, v105
	global_load_dwordx4 v[140:143], v189, s[12:13]
	s_add_u32 s14, s14, s17
	v_mov_b32_e32 v190, s14
	v_lshl_add_u32 v190, v190, 11, v105
	global_load_dwordx4 v[144:147], v190, s[12:13]
	s_add_u32 s14, s14, s17
	v_mov_b32_e32 v191, s14
	v_lshl_add_u32 v191, v191, 11, v105
	global_load_dwordx4 v[148:151], v191, s[12:13]
	s_add_u32 s14, s14, s17
	v_mov_b32_e32 v192, s14
	v_lshl_add_u32 v192, v192, 11, v105
	global_load_dwordx4 v[152:155], v192, s[12:13]
	s_add_u32 s14, s14, s17
	v_mov_b32_e32 v193, s14
	v_lshl_add_u32 v193, v193, 11, v105
	global_load_dwordx4 v[156:159], v193, s[12:13]
	s_add_u32 s14, s14, s17
	v_mov_b32_e32 v194, s14
	v_lshl_add_u32 v194, v194, 11, v105
	global_load_dwordx4 v[160:163], v194, s[12:13]
	s_add_u32 s14, s14, s17
	v_mov_b32_e32 v195, s14
	v_lshl_add_u32 v195, v195, 11, v105
	global_load_dwordx4 v[164:167], v195, s[12:13]
	s_add_u32 s14, s14, s17
	v_mov_b32_e32 v196, s14
	v_lshl_add_u32 v196, v196, 11, v105
	global_load_dwordx4 v[168:171], v196, s[12:13]
	s_add_u32 s14, s14, s17
	v_mov_b32_e32 v197, s14
	v_lshl_add_u32 v197, v197, 11, v105
	global_load_dwordx4 v[172:175], v197, s[12:13]
	s_add_u32 s14, s14, s17
	v_mov_b32_e32 v198, s14
	v_lshl_add_u32 v198, v198, 11, v105
	global_load_dwordx4 v[176:179], v198, s[12:13]
	s_add_u32 s14, s14, s17
	v_mov_b32_e32 v199, s14
	v_lshl_add_u32 v199, v199, 11, v105
	global_load_dwordx4 v[180:183], v199, s[12:13]
	s_add_u32 s14, s14, s17
	s_waitcnt vmcnt(15)
	v_lshlrev_b32_e32 v200, 16, v120
	v_and_b32_e32 v201, 0xffff0000, v120
	v_lshlrev_b32_e32 v202, 16, v121
	v_and_b32_e32 v203, 0xffff0000, v121
	v_lshlrev_b32_e32 v204, 16, v122
	v_and_b32_e32 v205, 0xffff0000, v122
	v_lshlrev_b32_e32 v206, 16, v123
	v_and_b32_e32 v207, 0xffff0000, v123
	v_pk_mul_f32 v[208:209], v[200:201], v[200:201]
	v_pk_mul_f32 v[210:211], v[202:203], v[202:203]
	v_pk_mul_f32 v[212:213], v[204:205], v[204:205]
	v_pk_mul_f32 v[214:215], v[206:207], v[206:207]
	v_add_f32_e32 v208, v208, v209
	v_add_f32_e32 v208, v210, v208
	v_add_f32_e32 v208, v211, v208
	v_add_f32_e32 v208, v212, v208
	v_add_f32_e32 v208, v213, v208
	v_add_f32_e32 v208, v214, v208
	v_add_f32_e32 v208, v215, v208
	s_nop 1
	v_add_f32_dpp v208, v208, v208 quad_perm:[1,0,3,2] row_mask:0xf bank_mask:0xf
	s_nop 1
	v_add_f32_dpp v208, v208, v208 quad_perm:[2,3,0,1] row_mask:0xf bank_mask:0xf
	s_nop 1
	v_mov_b32_dpp v209, v208 row_half_mirror row_mask:0xf bank_mask:0xf
	v_add_f32_e32 v208, v208, v209
	v_fmamk_f32 v208, v208, 0x3c800000, v114
	v_rsq_f32_e32 v208, v208
	s_nop 0
	v_mul_f32_e32 v200, v208, v200
	v_mul_f32_e32 v201, v208, v201
	v_mul_f32_e32 v202, v208, v202
	v_mul_f32_e32 v203, v208, v203
	v_mul_f32_e32 v204, v208, v204
	v_mul_f32_e32 v205, v208, v205
	v_mul_f32_e32 v206, v208, v206
	v_mul_f32_e32 v207, v208, v207
	v_mul_f32_e32 v200, v106, v200
	v_mul_f32_e32 v201, v107, v201
	v_mul_f32_e32 v202, v108, v202
	v_mul_f32_e32 v203, v109, v203
	v_mul_f32_e32 v204, v110, v204
	v_mul_f32_e32 v205, v111, v205
	v_mul_f32_e32 v206, v112, v206
	v_mul_f32_e32 v207, v113, v207
	v_cvt_pk_bf16_f32 v120, v200, v201
	v_cvt_pk_bf16_f32 v121, v202, v203
	v_cvt_pk_bf16_f32 v122, v204, v205
	v_cvt_pk_bf16_f32 v123, v206, v207
	global_store_dwordx4 v184, v[120:123], s[12:13]
	s_waitcnt vmcnt(15)
	v_lshlrev_b32_e32 v200, 16, v124
	v_and_b32_e32 v201, 0xffff0000, v124
	v_lshlrev_b32_e32 v202, 16, v125
	v_and_b32_e32 v203, 0xffff0000, v125
	v_lshlrev_b32_e32 v204, 16, v126
	v_and_b32_e32 v205, 0xffff0000, v126
	v_lshlrev_b32_e32 v206, 16, v127
	v_and_b32_e32 v207, 0xffff0000, v127
	v_pk_mul_f32 v[208:209], v[200:201], v[200:201]
	v_pk_mul_f32 v[210:211], v[202:203], v[202:203]
	v_pk_mul_f32 v[212:213], v[204:205], v[204:205]
	v_pk_mul_f32 v[214:215], v[206:207], v[206:207]
	v_add_f32_e32 v208, v208, v209
	v_add_f32_e32 v208, v210, v208
	v_add_f32_e32 v208, v211, v208
	v_add_f32_e32 v208, v212, v208
	v_add_f32_e32 v208, v213, v208
	v_add_f32_e32 v208, v214, v208
	v_add_f32_e32 v208, v215, v208
	s_nop 1
	v_add_f32_dpp v208, v208, v208 quad_perm:[1,0,3,2] row_mask:0xf bank_mask:0xf
	s_nop 1
	v_add_f32_dpp v208, v208, v208 quad_perm:[2,3,0,1] row_mask:0xf bank_mask:0xf
	s_nop 1
	v_mov_b32_dpp v209, v208 row_half_mirror row_mask:0xf bank_mask:0xf
	v_add_f32_e32 v208, v208, v209
	v_fmamk_f32 v208, v208, 0x3c800000, v114
	v_rsq_f32_e32 v208, v208
	s_nop 0
	v_mul_f32_e32 v200, v208, v200
	v_mul_f32_e32 v201, v208, v201
	v_mul_f32_e32 v202, v208, v202
	v_mul_f32_e32 v203, v208, v203
	v_mul_f32_e32 v204, v208, v204
	v_mul_f32_e32 v205, v208, v205
	v_mul_f32_e32 v206, v208, v206
	v_mul_f32_e32 v207, v208, v207
	v_mul_f32_e32 v200, v106, v200
	v_mul_f32_e32 v201, v107, v201
	v_mul_f32_e32 v202, v108, v202
	v_mul_f32_e32 v203, v109, v203
	v_mul_f32_e32 v204, v110, v204
	v_mul_f32_e32 v205, v111, v205
	v_mul_f32_e32 v206, v112, v206
	v_mul_f32_e32 v207, v113, v207
	v_cvt_pk_bf16_f32 v124, v200, v201
	v_cvt_pk_bf16_f32 v125, v202, v203
	v_cvt_pk_bf16_f32 v126, v204, v205
	v_cvt_pk_bf16_f32 v127, v206, v207
	global_store_dwordx4 v185, v[124:127], s[12:13]
	s_waitcnt vmcnt(15)
	v_lshlrev_b32_e32 v200, 16, v128
	v_and_b32_e32 v201, 0xffff0000, v128
	v_lshlrev_b32_e32 v202, 16, v129
	v_and_b32_e32 v203, 0xffff0000, v129
	v_lshlrev_b32_e32 v204, 16, v130
	v_and_b32_e32 v205, 0xffff0000, v130
	v_lshlrev_b32_e32 v206, 16, v131
	v_and_b32_e32 v207, 0xffff0000, v131
	v_pk_mul_f32 v[208:209], v[200:201], v[200:201]
	v_pk_mul_f32 v[210:211], v[202:203], v[202:203]
	v_pk_mul_f32 v[212:213], v[204:205], v[204:205]
	v_pk_mul_f32 v[214:215], v[206:207], v[206:207]
	v_add_f32_e32 v208, v208, v209
	v_add_f32_e32 v208, v210, v208
	v_add_f32_e32 v208, v211, v208
	v_add_f32_e32 v208, v212, v208
	v_add_f32_e32 v208, v213, v208
	v_add_f32_e32 v208, v214, v208
	v_add_f32_e32 v208, v215, v208
	s_nop 1
	v_add_f32_dpp v208, v208, v208 quad_perm:[1,0,3,2] row_mask:0xf bank_mask:0xf
	s_nop 1
	v_add_f32_dpp v208, v208, v208 quad_perm:[2,3,0,1] row_mask:0xf bank_mask:0xf
	s_nop 1
	v_mov_b32_dpp v209, v208 row_half_mirror row_mask:0xf bank_mask:0xf
	v_add_f32_e32 v208, v208, v209
	v_fmamk_f32 v208, v208, 0x3c800000, v114
	v_rsq_f32_e32 v208, v208
	s_nop 0
	v_mul_f32_e32 v200, v208, v200
	v_mul_f32_e32 v201, v208, v201
	v_mul_f32_e32 v202, v208, v202
	v_mul_f32_e32 v203, v208, v203
	v_mul_f32_e32 v204, v208, v204
	v_mul_f32_e32 v205, v208, v205
	v_mul_f32_e32 v206, v208, v206
	v_mul_f32_e32 v207, v208, v207
	v_mul_f32_e32 v200, v106, v200
	v_mul_f32_e32 v201, v107, v201
	v_mul_f32_e32 v202, v108, v202
	v_mul_f32_e32 v203, v109, v203
	v_mul_f32_e32 v204, v110, v204
	v_mul_f32_e32 v205, v111, v205
	v_mul_f32_e32 v206, v112, v206
	v_mul_f32_e32 v207, v113, v207
	v_cvt_pk_bf16_f32 v128, v200, v201
	v_cvt_pk_bf16_f32 v129, v202, v203
	v_cvt_pk_bf16_f32 v130, v204, v205
	v_cvt_pk_bf16_f32 v131, v206, v207
	global_store_dwordx4 v186, v[128:131], s[12:13]
	s_waitcnt vmcnt(15)
	v_lshlrev_b32_e32 v200, 16, v132
	v_and_b32_e32 v201, 0xffff0000, v132
	v_lshlrev_b32_e32 v202, 16, v133
	v_and_b32_e32 v203, 0xffff0000, v133
	v_lshlrev_b32_e32 v204, 16, v134
	v_and_b32_e32 v205, 0xffff0000, v134
	v_lshlrev_b32_e32 v206, 16, v135
	v_and_b32_e32 v207, 0xffff0000, v135
	v_pk_mul_f32 v[208:209], v[200:201], v[200:201]
	v_pk_mul_f32 v[210:211], v[202:203], v[202:203]
	v_pk_mul_f32 v[212:213], v[204:205], v[204:205]
	v_pk_mul_f32 v[214:215], v[206:207], v[206:207]
	v_add_f32_e32 v208, v208, v209
	v_add_f32_e32 v208, v210, v208
	v_add_f32_e32 v208, v211, v208
	v_add_f32_e32 v208, v212, v208
	v_add_f32_e32 v208, v213, v208
	v_add_f32_e32 v208, v214, v208
	v_add_f32_e32 v208, v215, v208
	s_nop 1
	v_add_f32_dpp v208, v208, v208 quad_perm:[1,0,3,2] row_mask:0xf bank_mask:0xf
	s_nop 1
	v_add_f32_dpp v208, v208, v208 quad_perm:[2,3,0,1] row_mask:0xf bank_mask:0xf
	s_nop 1
	v_mov_b32_dpp v209, v208 row_half_mirror row_mask:0xf bank_mask:0xf
	v_add_f32_e32 v208, v208, v209
	v_fmamk_f32 v208, v208, 0x3c800000, v114
	v_rsq_f32_e32 v208, v208
	s_nop 0
	v_mul_f32_e32 v200, v208, v200
	v_mul_f32_e32 v201, v208, v201
	v_mul_f32_e32 v202, v208, v202
	v_mul_f32_e32 v203, v208, v203
	v_mul_f32_e32 v204, v208, v204
	v_mul_f32_e32 v205, v208, v205
	v_mul_f32_e32 v206, v208, v206
	v_mul_f32_e32 v207, v208, v207
	v_mul_f32_e32 v200, v106, v200
	v_mul_f32_e32 v201, v107, v201
	v_mul_f32_e32 v202, v108, v202
	v_mul_f32_e32 v203, v109, v203
	v_mul_f32_e32 v204, v110, v204
	v_mul_f32_e32 v205, v111, v205
	v_mul_f32_e32 v206, v112, v206
	v_mul_f32_e32 v207, v113, v207
	v_cvt_pk_bf16_f32 v132, v200, v201
	v_cvt_pk_bf16_f32 v133, v202, v203
	v_cvt_pk_bf16_f32 v134, v204, v205
	v_cvt_pk_bf16_f32 v135, v206, v207
	global_store_dwordx4 v187, v[132:135], s[12:13]
	s_waitcnt vmcnt(15)
	v_lshlrev_b32_e32 v200, 16, v136
	v_and_b32_e32 v201, 0xffff0000, v136
	v_lshlrev_b32_e32 v202, 16, v137
	v_and_b32_e32 v203, 0xffff0000, v137
	v_lshlrev_b32_e32 v204, 16, v138
	v_and_b32_e32 v205, 0xffff0000, v138
	v_lshlrev_b32_e32 v206, 16, v139
	v_and_b32_e32 v207, 0xffff0000, v139
	v_pk_mul_f32 v[208:209], v[200:201], v[200:201]
	v_pk_mul_f32 v[210:211], v[202:203], v[202:203]
	v_pk_mul_f32 v[212:213], v[204:205], v[204:205]
	v_pk_mul_f32 v[214:215], v[206:207], v[206:207]
	v_add_f32_e32 v208, v208, v209
	v_add_f32_e32 v208, v210, v208
	v_add_f32_e32 v208, v211, v208
	v_add_f32_e32 v208, v212, v208
	v_add_f32_e32 v208, v213, v208
	v_add_f32_e32 v208, v214, v208
	v_add_f32_e32 v208, v215, v208
	s_nop 1
	v_add_f32_dpp v208, v208, v208 quad_perm:[1,0,3,2] row_mask:0xf bank_mask:0xf
	s_nop 1
	v_add_f32_dpp v208, v208, v208 quad_perm:[2,3,0,1] row_mask:0xf bank_mask:0xf
	s_nop 1
	v_mov_b32_dpp v209, v208 row_half_mirror row_mask:0xf bank_mask:0xf
	v_add_f32_e32 v208, v208, v209
	v_fmamk_f32 v208, v208, 0x3c800000, v114
	v_rsq_f32_e32 v208, v208
	s_nop 0
	v_mul_f32_e32 v200, v208, v200
	v_mul_f32_e32 v201, v208, v201
	v_mul_f32_e32 v202, v208, v202
	v_mul_f32_e32 v203, v208, v203
	v_mul_f32_e32 v204, v208, v204
	v_mul_f32_e32 v205, v208, v205
	v_mul_f32_e32 v206, v208, v206
	v_mul_f32_e32 v207, v208, v207
	v_mul_f32_e32 v200, v106, v200
	v_mul_f32_e32 v201, v107, v201
	v_mul_f32_e32 v202, v108, v202
	v_mul_f32_e32 v203, v109, v203
	v_mul_f32_e32 v204, v110, v204
	v_mul_f32_e32 v205, v111, v205
	v_mul_f32_e32 v206, v112, v206
	v_mul_f32_e32 v207, v113, v207
	v_cvt_pk_bf16_f32 v136, v200, v201
	v_cvt_pk_bf16_f32 v137, v202, v203
	v_cvt_pk_bf16_f32 v138, v204, v205
	v_cvt_pk_bf16_f32 v139, v206, v207
	global_store_dwordx4 v188, v[136:139], s[12:13]
	s_waitcnt vmcnt(15)
	v_lshlrev_b32_e32 v200, 16, v140
	v_and_b32_e32 v201, 0xffff0000, v140
	v_lshlrev_b32_e32 v202, 16, v141
	v_and_b32_e32 v203, 0xffff0000, v141
	v_lshlrev_b32_e32 v204, 16, v142
	v_and_b32_e32 v205, 0xffff0000, v142
	v_lshlrev_b32_e32 v206, 16, v143
	v_and_b32_e32 v207, 0xffff0000, v143
	v_pk_mul_f32 v[208:209], v[200:201], v[200:201]
	v_pk_mul_f32 v[210:211], v[202:203], v[202:203]
	v_pk_mul_f32 v[212:213], v[204:205], v[204:205]
	v_pk_mul_f32 v[214:215], v[206:207], v[206:207]
	v_add_f32_e32 v208, v208, v209
	v_add_f32_e32 v208, v210, v208
	v_add_f32_e32 v208, v211, v208
	v_add_f32_e32 v208, v212, v208
	v_add_f32_e32 v208, v213, v208
	v_add_f32_e32 v208, v214, v208
	v_add_f32_e32 v208, v215, v208
	s_nop 1
	v_add_f32_dpp v208, v208, v208 quad_perm:[1,0,3,2] row_mask:0xf bank_mask:0xf
	s_nop 1
	v_add_f32_dpp v208, v208, v208 quad_perm:[2,3,0,1] row_mask:0xf bank_mask:0xf
	s_nop 1
	v_mov_b32_dpp v209, v208 row_half_mirror row_mask:0xf bank_mask:0xf
	v_add_f32_e32 v208, v208, v209
	v_fmamk_f32 v208, v208, 0x3c800000, v114
	v_rsq_f32_e32 v208, v208
	s_nop 0
	v_mul_f32_e32 v200, v208, v200
	v_mul_f32_e32 v201, v208, v201
	v_mul_f32_e32 v202, v208, v202
	v_mul_f32_e32 v203, v208, v203
	v_mul_f32_e32 v204, v208, v204
	v_mul_f32_e32 v205, v208, v205
	v_mul_f32_e32 v206, v208, v206
	v_mul_f32_e32 v207, v208, v207
	v_mul_f32_e32 v200, v106, v200
	v_mul_f32_e32 v201, v107, v201
	v_mul_f32_e32 v202, v108, v202
	v_mul_f32_e32 v203, v109, v203
	v_mul_f32_e32 v204, v110, v204
	v_mul_f32_e32 v205, v111, v205
	v_mul_f32_e32 v206, v112, v206
	v_mul_f32_e32 v207, v113, v207
	v_cvt_pk_bf16_f32 v140, v200, v201
	v_cvt_pk_bf16_f32 v141, v202, v203
	v_cvt_pk_bf16_f32 v142, v204, v205
	v_cvt_pk_bf16_f32 v143, v206, v207
	global_store_dwordx4 v189, v[140:143], s[12:13]
	s_waitcnt vmcnt(15)
	v_lshlrev_b32_e32 v200, 16, v144
	v_and_b32_e32 v201, 0xffff0000, v144
	v_lshlrev_b32_e32 v202, 16, v145
	v_and_b32_e32 v203, 0xffff0000, v145
	v_lshlrev_b32_e32 v204, 16, v146
	v_and_b32_e32 v205, 0xffff0000, v146
	v_lshlrev_b32_e32 v206, 16, v147
	v_and_b32_e32 v207, 0xffff0000, v147
	v_pk_mul_f32 v[208:209], v[200:201], v[200:201]
	v_pk_mul_f32 v[210:211], v[202:203], v[202:203]
	v_pk_mul_f32 v[212:213], v[204:205], v[204:205]
	v_pk_mul_f32 v[214:215], v[206:207], v[206:207]
	v_add_f32_e32 v208, v208, v209
	v_add_f32_e32 v208, v210, v208
	v_add_f32_e32 v208, v211, v208
	v_add_f32_e32 v208, v212, v208
	v_add_f32_e32 v208, v213, v208
	v_add_f32_e32 v208, v214, v208
	v_add_f32_e32 v208, v215, v208
	s_nop 1
	v_add_f32_dpp v208, v208, v208 quad_perm:[1,0,3,2] row_mask:0xf bank_mask:0xf
	s_nop 1
	v_add_f32_dpp v208, v208, v208 quad_perm:[2,3,0,1] row_mask:0xf bank_mask:0xf
	s_nop 1
	v_mov_b32_dpp v209, v208 row_half_mirror row_mask:0xf bank_mask:0xf
	v_add_f32_e32 v208, v208, v209
	v_fmamk_f32 v208, v208, 0x3c800000, v114
	v_rsq_f32_e32 v208, v208
	s_nop 0
	v_mul_f32_e32 v200, v208, v200
	v_mul_f32_e32 v201, v208, v201
	v_mul_f32_e32 v202, v208, v202
	v_mul_f32_e32 v203, v208, v203
	v_mul_f32_e32 v204, v208, v204
	v_mul_f32_e32 v205, v208, v205
	v_mul_f32_e32 v206, v208, v206
	v_mul_f32_e32 v207, v208, v207
	v_mul_f32_e32 v200, v106, v200
	v_mul_f32_e32 v201, v107, v201
	v_mul_f32_e32 v202, v108, v202
	v_mul_f32_e32 v203, v109, v203
	v_mul_f32_e32 v204, v110, v204
	v_mul_f32_e32 v205, v111, v205
	v_mul_f32_e32 v206, v112, v206
	v_mul_f32_e32 v207, v113, v207
	v_cvt_pk_bf16_f32 v144, v200, v201
	v_cvt_pk_bf16_f32 v145, v202, v203
	v_cvt_pk_bf16_f32 v146, v204, v205
	v_cvt_pk_bf16_f32 v147, v206, v207
	global_store_dwordx4 v190, v[144:147], s[12:13]
	s_waitcnt vmcnt(15)
	v_lshlrev_b32_e32 v200, 16, v148
	v_and_b32_e32 v201, 0xffff0000, v148
	v_lshlrev_b32_e32 v202, 16, v149
	v_and_b32_e32 v203, 0xffff0000, v149
	v_lshlrev_b32_e32 v204, 16, v150
	v_and_b32_e32 v205, 0xffff0000, v150
	v_lshlrev_b32_e32 v206, 16, v151
	v_and_b32_e32 v207, 0xffff0000, v151
	v_pk_mul_f32 v[208:209], v[200:201], v[200:201]
	v_pk_mul_f32 v[210:211], v[202:203], v[202:203]
	v_pk_mul_f32 v[212:213], v[204:205], v[204:205]
	v_pk_mul_f32 v[214:215], v[206:207], v[206:207]
	v_add_f32_e32 v208, v208, v209
	v_add_f32_e32 v208, v210, v208
	v_add_f32_e32 v208, v211, v208
	v_add_f32_e32 v208, v212, v208
	v_add_f32_e32 v208, v213, v208
	v_add_f32_e32 v208, v214, v208
	v_add_f32_e32 v208, v215, v208
	s_nop 1
	v_add_f32_dpp v208, v208, v208 quad_perm:[1,0,3,2] row_mask:0xf bank_mask:0xf
	s_nop 1
	v_add_f32_dpp v208, v208, v208 quad_perm:[2,3,0,1] row_mask:0xf bank_mask:0xf
	s_nop 1
	v_mov_b32_dpp v209, v208 row_half_mirror row_mask:0xf bank_mask:0xf
	v_add_f32_e32 v208, v208, v209
	v_fmamk_f32 v208, v208, 0x3c800000, v114
	v_rsq_f32_e32 v208, v208
	s_nop 0
	v_mul_f32_e32 v200, v208, v200
	v_mul_f32_e32 v201, v208, v201
	v_mul_f32_e32 v202, v208, v202
	v_mul_f32_e32 v203, v208, v203
	v_mul_f32_e32 v204, v208, v204
	v_mul_f32_e32 v205, v208, v205
	v_mul_f32_e32 v206, v208, v206
	v_mul_f32_e32 v207, v208, v207
	v_mul_f32_e32 v200, v106, v200
	v_mul_f32_e32 v201, v107, v201
	v_mul_f32_e32 v202, v108, v202
	v_mul_f32_e32 v203, v109, v203
	v_mul_f32_e32 v204, v110, v204
	v_mul_f32_e32 v205, v111, v205
	v_mul_f32_e32 v206, v112, v206
	v_mul_f32_e32 v207, v113, v207
	v_cvt_pk_bf16_f32 v148, v200, v201
	v_cvt_pk_bf16_f32 v149, v202, v203
	v_cvt_pk_bf16_f32 v150, v204, v205
	v_cvt_pk_bf16_f32 v151, v206, v207
	global_store_dwordx4 v191, v[148:151], s[12:13]
	s_waitcnt vmcnt(15)
	v_lshlrev_b32_e32 v200, 16, v152
	v_and_b32_e32 v201, 0xffff0000, v152
	v_lshlrev_b32_e32 v202, 16, v153
	v_and_b32_e32 v203, 0xffff0000, v153
	v_lshlrev_b32_e32 v204, 16, v154
	v_and_b32_e32 v205, 0xffff0000, v154
	v_lshlrev_b32_e32 v206, 16, v155
	v_and_b32_e32 v207, 0xffff0000, v155
	v_pk_mul_f32 v[208:209], v[200:201], v[200:201]
	v_pk_mul_f32 v[210:211], v[202:203], v[202:203]
	v_pk_mul_f32 v[212:213], v[204:205], v[204:205]
	v_pk_mul_f32 v[214:215], v[206:207], v[206:207]
	v_add_f32_e32 v208, v208, v209
	v_add_f32_e32 v208, v210, v208
	v_add_f32_e32 v208, v211, v208
	v_add_f32_e32 v208, v212, v208
	v_add_f32_e32 v208, v213, v208
	v_add_f32_e32 v208, v214, v208
	v_add_f32_e32 v208, v215, v208
	s_nop 1
	v_add_f32_dpp v208, v208, v208 quad_perm:[1,0,3,2] row_mask:0xf bank_mask:0xf
	s_nop 1
	v_add_f32_dpp v208, v208, v208 quad_perm:[2,3,0,1] row_mask:0xf bank_mask:0xf
	s_nop 1
	v_mov_b32_dpp v209, v208 row_half_mirror row_mask:0xf bank_mask:0xf
	v_add_f32_e32 v208, v208, v209
	v_fmamk_f32 v208, v208, 0x3c800000, v114
	v_rsq_f32_e32 v208, v208
	s_nop 0
	v_mul_f32_e32 v200, v208, v200
	v_mul_f32_e32 v201, v208, v201
	v_mul_f32_e32 v202, v208, v202
	v_mul_f32_e32 v203, v208, v203
	v_mul_f32_e32 v204, v208, v204
	v_mul_f32_e32 v205, v208, v205
	v_mul_f32_e32 v206, v208, v206
	v_mul_f32_e32 v207, v208, v207
	v_mul_f32_e32 v200, v106, v200
	v_mul_f32_e32 v201, v107, v201
	v_mul_f32_e32 v202, v108, v202
	v_mul_f32_e32 v203, v109, v203
	v_mul_f32_e32 v204, v110, v204
	v_mul_f32_e32 v205, v111, v205
	v_mul_f32_e32 v206, v112, v206
	v_mul_f32_e32 v207, v113, v207
	v_cvt_pk_bf16_f32 v152, v200, v201
	v_cvt_pk_bf16_f32 v153, v202, v203
	v_cvt_pk_bf16_f32 v154, v204, v205
	v_cvt_pk_bf16_f32 v155, v206, v207
	global_store_dwordx4 v192, v[152:155], s[12:13]
	s_waitcnt vmcnt(15)
	v_lshlrev_b32_e32 v200, 16, v156
	v_and_b32_e32 v201, 0xffff0000, v156
	v_lshlrev_b32_e32 v202, 16, v157
	v_and_b32_e32 v203, 0xffff0000, v157
	v_lshlrev_b32_e32 v204, 16, v158
	v_and_b32_e32 v205, 0xffff0000, v158
	v_lshlrev_b32_e32 v206, 16, v159
	v_and_b32_e32 v207, 0xffff0000, v159
	v_pk_mul_f32 v[208:209], v[200:201], v[200:201]
	v_pk_mul_f32 v[210:211], v[202:203], v[202:203]
	v_pk_mul_f32 v[212:213], v[204:205], v[204:205]
	v_pk_mul_f32 v[214:215], v[206:207], v[206:207]
	v_add_f32_e32 v208, v208, v209
	v_add_f32_e32 v208, v210, v208
	v_add_f32_e32 v208, v211, v208
	v_add_f32_e32 v208, v212, v208
	v_add_f32_e32 v208, v213, v208
	v_add_f32_e32 v208, v214, v208
	v_add_f32_e32 v208, v215, v208
	s_nop 1
	v_add_f32_dpp v208, v208, v208 quad_perm:[1,0,3,2] row_mask:0xf bank_mask:0xf
	s_nop 1
	v_add_f32_dpp v208, v208, v208 quad_perm:[2,3,0,1] row_mask:0xf bank_mask:0xf
	s_nop 1
	v_mov_b32_dpp v209, v208 row_half_mirror row_mask:0xf bank_mask:0xf
	v_add_f32_e32 v208, v208, v209
	v_fmamk_f32 v208, v208, 0x3c800000, v114
	v_rsq_f32_e32 v208, v208
	s_nop 0
	v_mul_f32_e32 v200, v208, v200
	v_mul_f32_e32 v201, v208, v201
	v_mul_f32_e32 v202, v208, v202
	v_mul_f32_e32 v203, v208, v203
	v_mul_f32_e32 v204, v208, v204
	v_mul_f32_e32 v205, v208, v205
	v_mul_f32_e32 v206, v208, v206
	v_mul_f32_e32 v207, v208, v207
	v_mul_f32_e32 v200, v106, v200
	v_mul_f32_e32 v201, v107, v201
	v_mul_f32_e32 v202, v108, v202
	v_mul_f32_e32 v203, v109, v203
	v_mul_f32_e32 v204, v110, v204
	v_mul_f32_e32 v205, v111, v205
	v_mul_f32_e32 v206, v112, v206
	v_mul_f32_e32 v207, v113, v207
	v_cvt_pk_bf16_f32 v156, v200, v201
	v_cvt_pk_bf16_f32 v157, v202, v203
	v_cvt_pk_bf16_f32 v158, v204, v205
	v_cvt_pk_bf16_f32 v159, v206, v207
	global_store_dwordx4 v193, v[156:159], s[12:13]
	s_waitcnt vmcnt(15)
	v_lshlrev_b32_e32 v200, 16, v160
	v_and_b32_e32 v201, 0xffff0000, v160
	v_lshlrev_b32_e32 v202, 16, v161
	v_and_b32_e32 v203, 0xffff0000, v161
	v_lshlrev_b32_e32 v204, 16, v162
	v_and_b32_e32 v205, 0xffff0000, v162
	v_lshlrev_b32_e32 v206, 16, v163
	v_and_b32_e32 v207, 0xffff0000, v163
	v_pk_mul_f32 v[208:209], v[200:201], v[200:201]
	v_pk_mul_f32 v[210:211], v[202:203], v[202:203]
	v_pk_mul_f32 v[212:213], v[204:205], v[204:205]
	v_pk_mul_f32 v[214:215], v[206:207], v[206:207]
	v_add_f32_e32 v208, v208, v209
	v_add_f32_e32 v208, v210, v208
	v_add_f32_e32 v208, v211, v208
	v_add_f32_e32 v208, v212, v208
	v_add_f32_e32 v208, v213, v208
	v_add_f32_e32 v208, v214, v208
	v_add_f32_e32 v208, v215, v208
	s_nop 1
	v_add_f32_dpp v208, v208, v208 quad_perm:[1,0,3,2] row_mask:0xf bank_mask:0xf
	s_nop 1
	v_add_f32_dpp v208, v208, v208 quad_perm:[2,3,0,1] row_mask:0xf bank_mask:0xf
	s_nop 1
	v_mov_b32_dpp v209, v208 row_half_mirror row_mask:0xf bank_mask:0xf
	v_add_f32_e32 v208, v208, v209
	v_fmamk_f32 v208, v208, 0x3c800000, v114
	v_rsq_f32_e32 v208, v208
	s_nop 0
	v_mul_f32_e32 v200, v208, v200
	v_mul_f32_e32 v201, v208, v201
	v_mul_f32_e32 v202, v208, v202
	v_mul_f32_e32 v203, v208, v203
	v_mul_f32_e32 v204, v208, v204
	v_mul_f32_e32 v205, v208, v205
	v_mul_f32_e32 v206, v208, v206
	v_mul_f32_e32 v207, v208, v207
	v_mul_f32_e32 v200, v106, v200
	v_mul_f32_e32 v201, v107, v201
	v_mul_f32_e32 v202, v108, v202
	v_mul_f32_e32 v203, v109, v203
	v_mul_f32_e32 v204, v110, v204
	v_mul_f32_e32 v205, v111, v205
	v_mul_f32_e32 v206, v112, v206
	v_mul_f32_e32 v207, v113, v207
	v_cvt_pk_bf16_f32 v160, v200, v201
	v_cvt_pk_bf16_f32 v161, v202, v203
	v_cvt_pk_bf16_f32 v162, v204, v205
	v_cvt_pk_bf16_f32 v163, v206, v207
	global_store_dwordx4 v194, v[160:163], s[12:13]
	s_waitcnt vmcnt(15)
	v_lshlrev_b32_e32 v200, 16, v164
	v_and_b32_e32 v201, 0xffff0000, v164
	v_lshlrev_b32_e32 v202, 16, v165
	v_and_b32_e32 v203, 0xffff0000, v165
	v_lshlrev_b32_e32 v204, 16, v166
	v_and_b32_e32 v205, 0xffff0000, v166
	v_lshlrev_b32_e32 v206, 16, v167
	v_and_b32_e32 v207, 0xffff0000, v167
	v_pk_mul_f32 v[208:209], v[200:201], v[200:201]
	v_pk_mul_f32 v[210:211], v[202:203], v[202:203]
	v_pk_mul_f32 v[212:213], v[204:205], v[204:205]
	v_pk_mul_f32 v[214:215], v[206:207], v[206:207]
	v_add_f32_e32 v208, v208, v209
	v_add_f32_e32 v208, v210, v208
	v_add_f32_e32 v208, v211, v208
	v_add_f32_e32 v208, v212, v208
	v_add_f32_e32 v208, v213, v208
	v_add_f32_e32 v208, v214, v208
	v_add_f32_e32 v208, v215, v208
	s_nop 1
	v_add_f32_dpp v208, v208, v208 quad_perm:[1,0,3,2] row_mask:0xf bank_mask:0xf
	s_nop 1
	v_add_f32_dpp v208, v208, v208 quad_perm:[2,3,0,1] row_mask:0xf bank_mask:0xf
	s_nop 1
	v_mov_b32_dpp v209, v208 row_half_mirror row_mask:0xf bank_mask:0xf
	v_add_f32_e32 v208, v208, v209
	v_fmamk_f32 v208, v208, 0x3c800000, v114
	v_rsq_f32_e32 v208, v208
	s_nop 0
	v_mul_f32_e32 v200, v208, v200
	v_mul_f32_e32 v201, v208, v201
	v_mul_f32_e32 v202, v208, v202
	v_mul_f32_e32 v203, v208, v203
	v_mul_f32_e32 v204, v208, v204
	v_mul_f32_e32 v205, v208, v205
	v_mul_f32_e32 v206, v208, v206
	v_mul_f32_e32 v207, v208, v207
	v_mul_f32_e32 v200, v106, v200
	v_mul_f32_e32 v201, v107, v201
	v_mul_f32_e32 v202, v108, v202
	v_mul_f32_e32 v203, v109, v203
	v_mul_f32_e32 v204, v110, v204
	v_mul_f32_e32 v205, v111, v205
	v_mul_f32_e32 v206, v112, v206
	v_mul_f32_e32 v207, v113, v207
	v_cvt_pk_bf16_f32 v164, v200, v201
	v_cvt_pk_bf16_f32 v165, v202, v203
	v_cvt_pk_bf16_f32 v166, v204, v205
	v_cvt_pk_bf16_f32 v167, v206, v207
	global_store_dwordx4 v195, v[164:167], s[12:13]
	s_waitcnt vmcnt(15)
	v_lshlrev_b32_e32 v200, 16, v168
	v_and_b32_e32 v201, 0xffff0000, v168
	v_lshlrev_b32_e32 v202, 16, v169
	v_and_b32_e32 v203, 0xffff0000, v169
	v_lshlrev_b32_e32 v204, 16, v170
	v_and_b32_e32 v205, 0xffff0000, v170
	v_lshlrev_b32_e32 v206, 16, v171
	v_and_b32_e32 v207, 0xffff0000, v171
	v_pk_mul_f32 v[208:209], v[200:201], v[200:201]
	v_pk_mul_f32 v[210:211], v[202:203], v[202:203]
	v_pk_mul_f32 v[212:213], v[204:205], v[204:205]
	v_pk_mul_f32 v[214:215], v[206:207], v[206:207]
	v_add_f32_e32 v208, v208, v209
	v_add_f32_e32 v208, v210, v208
	v_add_f32_e32 v208, v211, v208
	v_add_f32_e32 v208, v212, v208
	v_add_f32_e32 v208, v213, v208
	v_add_f32_e32 v208, v214, v208
	v_add_f32_e32 v208, v215, v208
	s_nop 1
	v_add_f32_dpp v208, v208, v208 quad_perm:[1,0,3,2] row_mask:0xf bank_mask:0xf
	s_nop 1
	v_add_f32_dpp v208, v208, v208 quad_perm:[2,3,0,1] row_mask:0xf bank_mask:0xf
	s_nop 1
	v_mov_b32_dpp v209, v208 row_half_mirror row_mask:0xf bank_mask:0xf
	v_add_f32_e32 v208, v208, v209
	v_fmamk_f32 v208, v208, 0x3c800000, v114
	v_rsq_f32_e32 v208, v208
	s_nop 0
	v_mul_f32_e32 v200, v208, v200
	v_mul_f32_e32 v201, v208, v201
	v_mul_f32_e32 v202, v208, v202
	v_mul_f32_e32 v203, v208, v203
	v_mul_f32_e32 v204, v208, v204
	v_mul_f32_e32 v205, v208, v205
	v_mul_f32_e32 v206, v208, v206
	v_mul_f32_e32 v207, v208, v207
	v_mul_f32_e32 v200, v106, v200
	v_mul_f32_e32 v201, v107, v201
	v_mul_f32_e32 v202, v108, v202
	v_mul_f32_e32 v203, v109, v203
	v_mul_f32_e32 v204, v110, v204
	v_mul_f32_e32 v205, v111, v205
	v_mul_f32_e32 v206, v112, v206
	v_mul_f32_e32 v207, v113, v207
	v_cvt_pk_bf16_f32 v168, v200, v201
	v_cvt_pk_bf16_f32 v169, v202, v203
	v_cvt_pk_bf16_f32 v170, v204, v205
	v_cvt_pk_bf16_f32 v171, v206, v207
	global_store_dwordx4 v196, v[168:171], s[12:13]
	s_waitcnt vmcnt(15)
	v_lshlrev_b32_e32 v200, 16, v172
	v_and_b32_e32 v201, 0xffff0000, v172
	v_lshlrev_b32_e32 v202, 16, v173
	v_and_b32_e32 v203, 0xffff0000, v173
	v_lshlrev_b32_e32 v204, 16, v174
	v_and_b32_e32 v205, 0xffff0000, v174
	v_lshlrev_b32_e32 v206, 16, v175
	v_and_b32_e32 v207, 0xffff0000, v175
	v_pk_mul_f32 v[208:209], v[200:201], v[200:201]
	v_pk_mul_f32 v[210:211], v[202:203], v[202:203]
	v_pk_mul_f32 v[212:213], v[204:205], v[204:205]
	v_pk_mul_f32 v[214:215], v[206:207], v[206:207]
	v_add_f32_e32 v208, v208, v209
	v_add_f32_e32 v208, v210, v208
	v_add_f32_e32 v208, v211, v208
	v_add_f32_e32 v208, v212, v208
	v_add_f32_e32 v208, v213, v208
	v_add_f32_e32 v208, v214, v208
	v_add_f32_e32 v208, v215, v208
	s_nop 1
	v_add_f32_dpp v208, v208, v208 quad_perm:[1,0,3,2] row_mask:0xf bank_mask:0xf
	s_nop 1
	v_add_f32_dpp v208, v208, v208 quad_perm:[2,3,0,1] row_mask:0xf bank_mask:0xf
	s_nop 1
	v_mov_b32_dpp v209, v208 row_half_mirror row_mask:0xf bank_mask:0xf
	v_add_f32_e32 v208, v208, v209
	v_fmamk_f32 v208, v208, 0x3c800000, v114
	v_rsq_f32_e32 v208, v208
	s_nop 0
	v_mul_f32_e32 v200, v208, v200
	v_mul_f32_e32 v201, v208, v201
	v_mul_f32_e32 v202, v208, v202
	v_mul_f32_e32 v203, v208, v203
	v_mul_f32_e32 v204, v208, v204
	v_mul_f32_e32 v205, v208, v205
	v_mul_f32_e32 v206, v208, v206
	v_mul_f32_e32 v207, v208, v207
	v_mul_f32_e32 v200, v106, v200
	v_mul_f32_e32 v201, v107, v201
	v_mul_f32_e32 v202, v108, v202
	v_mul_f32_e32 v203, v109, v203
	v_mul_f32_e32 v204, v110, v204
	v_mul_f32_e32 v205, v111, v205
	v_mul_f32_e32 v206, v112, v206
	v_mul_f32_e32 v207, v113, v207
	v_cvt_pk_bf16_f32 v172, v200, v201
	v_cvt_pk_bf16_f32 v173, v202, v203
	v_cvt_pk_bf16_f32 v174, v204, v205
	v_cvt_pk_bf16_f32 v175, v206, v207
	global_store_dwordx4 v197, v[172:175], s[12:13]
	s_waitcnt vmcnt(15)
	v_lshlrev_b32_e32 v200, 16, v176
	v_and_b32_e32 v201, 0xffff0000, v176
	v_lshlrev_b32_e32 v202, 16, v177
	v_and_b32_e32 v203, 0xffff0000, v177
	v_lshlrev_b32_e32 v204, 16, v178
	v_and_b32_e32 v205, 0xffff0000, v178
	v_lshlrev_b32_e32 v206, 16, v179
	v_and_b32_e32 v207, 0xffff0000, v179
	v_pk_mul_f32 v[208:209], v[200:201], v[200:201]
	v_pk_mul_f32 v[210:211], v[202:203], v[202:203]
	v_pk_mul_f32 v[212:213], v[204:205], v[204:205]
	v_pk_mul_f32 v[214:215], v[206:207], v[206:207]
	v_add_f32_e32 v208, v208, v209
	v_add_f32_e32 v208, v210, v208
	v_add_f32_e32 v208, v211, v208
	v_add_f32_e32 v208, v212, v208
	v_add_f32_e32 v208, v213, v208
	v_add_f32_e32 v208, v214, v208
	v_add_f32_e32 v208, v215, v208
	s_nop 1
	v_add_f32_dpp v208, v208, v208 quad_perm:[1,0,3,2] row_mask:0xf bank_mask:0xf
	s_nop 1
	v_add_f32_dpp v208, v208, v208 quad_perm:[2,3,0,1] row_mask:0xf bank_mask:0xf
	s_nop 1
	v_mov_b32_dpp v209, v208 row_half_mirror row_mask:0xf bank_mask:0xf
	v_add_f32_e32 v208, v208, v209
	v_fmamk_f32 v208, v208, 0x3c800000, v114
	v_rsq_f32_e32 v208, v208
	s_nop 0
	v_mul_f32_e32 v200, v208, v200
	v_mul_f32_e32 v201, v208, v201
	v_mul_f32_e32 v202, v208, v202
	v_mul_f32_e32 v203, v208, v203
	v_mul_f32_e32 v204, v208, v204
	v_mul_f32_e32 v205, v208, v205
	v_mul_f32_e32 v206, v208, v206
	v_mul_f32_e32 v207, v208, v207
	v_mul_f32_e32 v200, v106, v200
	v_mul_f32_e32 v201, v107, v201
	v_mul_f32_e32 v202, v108, v202
	v_mul_f32_e32 v203, v109, v203
	v_mul_f32_e32 v204, v110, v204
	v_mul_f32_e32 v205, v111, v205
	v_mul_f32_e32 v206, v112, v206
	v_mul_f32_e32 v207, v113, v207
	v_cvt_pk_bf16_f32 v176, v200, v201
	v_cvt_pk_bf16_f32 v177, v202, v203
	v_cvt_pk_bf16_f32 v178, v204, v205
	v_cvt_pk_bf16_f32 v179, v206, v207
	global_store_dwordx4 v198, v[176:179], s[12:13]
	s_waitcnt vmcnt(15)
	v_lshlrev_b32_e32 v200, 16, v180
	v_and_b32_e32 v201, 0xffff0000, v180
	v_lshlrev_b32_e32 v202, 16, v181
	v_and_b32_e32 v203, 0xffff0000, v181
	v_lshlrev_b32_e32 v204, 16, v182
	v_and_b32_e32 v205, 0xffff0000, v182
	v_lshlrev_b32_e32 v206, 16, v183
	v_and_b32_e32 v207, 0xffff0000, v183
	v_pk_mul_f32 v[208:209], v[200:201], v[200:201]
	v_pk_mul_f32 v[210:211], v[202:203], v[202:203]
	v_pk_mul_f32 v[212:213], v[204:205], v[204:205]
	v_pk_mul_f32 v[214:215], v[206:207], v[206:207]
	v_add_f32_e32 v208, v208, v209
	v_add_f32_e32 v208, v210, v208
	v_add_f32_e32 v208, v211, v208
	v_add_f32_e32 v208, v212, v208
	v_add_f32_e32 v208, v213, v208
	v_add_f32_e32 v208, v214, v208
	v_add_f32_e32 v208, v215, v208
	s_nop 1
	v_add_f32_dpp v208, v208, v208 quad_perm:[1,0,3,2] row_mask:0xf bank_mask:0xf
	s_nop 1
	v_add_f32_dpp v208, v208, v208 quad_perm:[2,3,0,1] row_mask:0xf bank_mask:0xf
	s_nop 1
	v_mov_b32_dpp v209, v208 row_half_mirror row_mask:0xf bank_mask:0xf
	v_add_f32_e32 v208, v208, v209
	v_fmamk_f32 v208, v208, 0x3c800000, v114
	v_rsq_f32_e32 v208, v208
	s_nop 0
	v_mul_f32_e32 v200, v208, v200
	v_mul_f32_e32 v201, v208, v201
	v_mul_f32_e32 v202, v208, v202
	v_mul_f32_e32 v203, v208, v203
	v_mul_f32_e32 v204, v208, v204
	v_mul_f32_e32 v205, v208, v205
	v_mul_f32_e32 v206, v208, v206
	v_mul_f32_e32 v207, v208, v207
	v_mul_f32_e32 v200, v106, v200
	v_mul_f32_e32 v201, v107, v201
	v_mul_f32_e32 v202, v108, v202
	v_mul_f32_e32 v203, v109, v203
	v_mul_f32_e32 v204, v110, v204
	v_mul_f32_e32 v205, v111, v205
	v_mul_f32_e32 v206, v112, v206
	v_mul_f32_e32 v207, v113, v207
	v_cvt_pk_bf16_f32 v180, v200, v201
	v_cvt_pk_bf16_f32 v181, v202, v203
	v_cvt_pk_bf16_f32 v182, v204, v205
	v_cvt_pk_bf16_f32 v183, v206, v207
	global_store_dwordx4 v199, v[180:183], s[12:13]
	s_lshl_b32 s15, s17, 4
	s_add_u32 s16, s16, s15
	s_branch .Lkn_loop
.Lkn_slow:
	s_cmp_ge_u32 s16, 0x8000
	s_cbranch_scc1 .Lkn_done
	s_mov_b32 s14, s16
	s_cmp_ge_u32 s14, 0x8000
	s_cbranch_scc1 .Lkn_ld_end
	v_mov_b32_e32 v184, s14
	v_lshl_add_u32 v184, v184, 11, v105
	global_load_dwordx4 v[120:123], v184, s[12:13]
	s_add_u32 s14, s14, s17
	s_cmp_ge_u32 s14, 0x8000
	s_cbranch_scc1 .Lkn_ld_end
	v_mov_b32_e32 v185, s14
	v_lshl_add_u32 v185, v185, 11, v105
	global_load_dwordx4 v[124:127], v185, s[12:13]
	s_add_u32 s14, s14, s17
	s_cmp_ge_u32 s14, 0x8000
	s_cbranch_scc1 .Lkn_ld_end
	v_mov_b32_e32 v186, s14
	v_lshl_add_u32 v186, v186, 11, v105
	global_load_dwordx4 v[128:131], v186, s[12:13]
	s_add_u32 s14, s14, s17
	s_cmp_ge_u32 s14, 0x8000
	s_cbranch_scc1 .Lkn_ld_end
	v_mov_b32_e32 v187, s14
	v_lshl_add_u32 v187, v187, 11, v105
	global_load_dwordx4 v[132:135], v187, s[12:13]
	s_add_u32 s14, s14, s17
	s_cmp_ge_u32 s14, 0x8000
	s_cbranch_scc1 .Lkn_ld_end
	v_mov_b32_e32 v188, s14
	v_lshl_add_u32 v188, v188, 11, v105
	global_load_dwordx4 v[136:139], v188, s[12:13]
	s_add_u32 s14, s14, s17
	s_cmp_ge_u32 s14, 0x8000
	s_cbranch_scc1 .Lkn_ld_end
	v_mov_b32_e32 v189, s14
	v_lshl_add_u32 v189, v189, 11, v105
	global_load_dwordx4 v[140:143], v189, s[12:13]
	s_add_u32 s14, s14, s17
	s_cmp_ge_u32 s14, 0x8000
	s_cbranch_scc1 .Lkn_ld_end
	v_mov_b32_e32 v190, s14
	v_lshl_add_u32 v190, v190, 11, v105
	global_load_dwordx4 v[144:147], v190, s[12:13]
	s_add_u32 s14, s14, s17
	s_cmp_ge_u32 s14, 0x8000
	s_cbranch_scc1 .Lkn_ld_end
	v_mov_b32_e32 v191, s14
	v_lshl_add_u32 v191, v191, 11, v105
	global_load_dwordx4 v[148:151], v191, s[12:13]
	s_add_u32 s14, s14, s17
.Lkn_ld_end:
	s_waitcnt vmcnt(0)
	s_mov_b32 s14, s16
	s_cmp_ge_u32 s14, 0x8000
	s_cbranch_scc1 .Lkn_st_end
	v_lshlrev_b32_e32 v200, 16, v120
	v_and_b32_e32 v201, 0xffff0000, v120
	v_lshlrev_b32_e32 v202, 16, v121
	v_and_b32_e32 v203, 0xffff0000, v121
	v_lshlrev_b32_e32 v204, 16, v122
	v_and_b32_e32 v205, 0xffff0000, v122
	v_lshlrev_b32_e32 v206, 16, v123
	v_and_b32_e32 v207, 0xffff0000, v123
	v_pk_mul_f32 v[208:209], v[200:201], v[200:201]
	v_pk_mul_f32 v[210:211], v[202:203], v[202:203]
	v_pk_mul_f32 v[212:213], v[204:205], v[204:205]
	v_pk_mul_f32 v[214:215], v[206:207], v[206:207]
	v_add_f32_e32 v208, v208, v209
	v_add_f32_e32 v208, v210, v208
	v_add_f32_e32 v208, v211, v208
	v_add_f32_e32 v208, v212, v208
	v_add_f32_e32 v208, v213, v208
	v_add_f32_e32 v208, v214, v208
	v_add_f32_e32 v208, v215, v208
	s_nop 1
	v_add_f32_dpp v208, v208, v208 quad_perm:[1,0,3,2] row_mask:0xf bank_mask:0xf
	s_nop 1
	v_add_f32_dpp v208, v208, v208 quad_perm:[2,3,0,1] row_mask:0xf bank_mask:0xf
	s_nop 1
	v_mov_b32_dpp v209, v208 row_half_mirror row_mask:0xf bank_mask:0xf
	v_add_f32_e32 v208, v208, v209
	v_fmamk_f32 v208, v208, 0x3c800000, v114
	v_rsq_f32_e32 v208, v208
	s_nop 0
	v_mul_f32_e32 v200, v208, v200
	v_mul_f32_e32 v201, v208, v201
	v_mul_f32_e32 v202, v208, v202
	v_mul_f32_e32 v203, v208, v203
	v_mul_f32_e32 v204, v208, v204
	v_mul_f32_e32 v205, v208, v205
	v_mul_f32_e32 v206, v208, v206
	v_mul_f32_e32 v207, v208, v207
	v_mul_f32_e32 v200, v106, v200
	v_mul_f32_e32 v201, v107, v201
	v_mul_f32_e32 v202, v108, v202
	v_mul_f32_e32 v203, v109, v203
	v_mul_f32_e32 v204, v110, v204
	v_mul_f32_e32 v205, v111, v205
	v_mul_f32_e32 v206, v112, v206
	v_mul_f32_e32 v207, v113, v207
	v_cvt_pk_bf16_f32 v120, v200, v201
	v_cvt_pk_bf16_f32 v121, v202, v203
	v_cvt_pk_bf16_f32 v122, v204, v205
	v_cvt_pk_bf16_f32 v123, v206, v207
	global_store_dwordx4 v184, v[120:123], s[12:13]
	s_add_u32 s14, s14, s17
	s_cmp_ge_u32 s14, 0x8000
	s_cbranch_scc1 .Lkn_st_end
	v_lshlrev_b32_e32 v200, 16, v124
	v_and_b32_e32 v201, 0xffff0000, v124
	v_lshlrev_b32_e32 v202, 16, v125
	v_and_b32_e32 v203, 0xffff0000, v125
	v_lshlrev_b32_e32 v204, 16, v126
	v_and_b32_e32 v205, 0xffff0000, v126
	v_lshlrev_b32_e32 v206, 16, v127
	v_and_b32_e32 v207, 0xffff0000, v127
	v_pk_mul_f32 v[208:209], v[200:201], v[200:201]
	v_pk_mul_f32 v[210:211], v[202:203], v[202:203]
	v_pk_mul_f32 v[212:213], v[204:205], v[204:205]
	v_pk_mul_f32 v[214:215], v[206:207], v[206:207]
	v_add_f32_e32 v208, v208, v209
	v_add_f32_e32 v208, v210, v208
	v_add_f32_e32 v208, v211, v208
	v_add_f32_e32 v208, v212, v208
	v_add_f32_e32 v208, v213, v208
	v_add_f32_e32 v208, v214, v208
	v_add_f32_e32 v208, v215, v208
	s_nop 1
	v_add_f32_dpp v208, v208, v208 quad_perm:[1,0,3,2] row_mask:0xf bank_mask:0xf
	s_nop 1
	v_add_f32_dpp v208, v208, v208 quad_perm:[2,3,0,1] row_mask:0xf bank_mask:0xf
	s_nop 1
	v_mov_b32_dpp v209, v208 row_half_mirror row_mask:0xf bank_mask:0xf
	v_add_f32_e32 v208, v208, v209
	v_fmamk_f32 v208, v208, 0x3c800000, v114
	v_rsq_f32_e32 v208, v208
	s_nop 0
	v_mul_f32_e32 v200, v208, v200
	v_mul_f32_e32 v201, v208, v201
	v_mul_f32_e32 v202, v208, v202
	v_mul_f32_e32 v203, v208, v203
	v_mul_f32_e32 v204, v208, v204
	v_mul_f32_e32 v205, v208, v205
	v_mul_f32_e32 v206, v208, v206
	v_mul_f32_e32 v207, v208, v207
	v_mul_f32_e32 v200, v106, v200
	v_mul_f32_e32 v201, v107, v201
	v_mul_f32_e32 v202, v108, v202
	v_mul_f32_e32 v203, v109, v203
	v_mul_f32_e32 v204, v110, v204
	v_mul_f32_e32 v205, v111, v205
	v_mul_f32_e32 v206, v112, v206
	v_mul_f32_e32 v207, v113, v207
	v_cvt_pk_bf16_f32 v124, v200, v201
	v_cvt_pk_bf16_f32 v125, v202, v203
	v_cvt_pk_bf16_f32 v126, v204, v205
	v_cvt_pk_bf16_f32 v127, v206, v207
	global_store_dwordx4 v185, v[124:127], s[12:13]
	s_add_u32 s14, s14, s17
	s_cmp_ge_u32 s14, 0x8000
	s_cbranch_scc1 .Lkn_st_end
	v_lshlrev_b32_e32 v200, 16, v128
	v_and_b32_e32 v201, 0xffff0000, v128
	v_lshlrev_b32_e32 v202, 16, v129
	v_and_b32_e32 v203, 0xffff0000, v129
	v_lshlrev_b32_e32 v204, 16, v130
	v_and_b32_e32 v205, 0xffff0000, v130
	v_lshlrev_b32_e32 v206, 16, v131
	v_and_b32_e32 v207, 0xffff0000, v131
	v_pk_mul_f32 v[208:209], v[200:201], v[200:201]
	v_pk_mul_f32 v[210:211], v[202:203], v[202:203]
	v_pk_mul_f32 v[212:213], v[204:205], v[204:205]
	v_pk_mul_f32 v[214:215], v[206:207], v[206:207]
	v_add_f32_e32 v208, v208, v209
	v_add_f32_e32 v208, v210, v208
	v_add_f32_e32 v208, v211, v208
	v_add_f32_e32 v208, v212, v208
	v_add_f32_e32 v208, v213, v208
	v_add_f32_e32 v208, v214, v208
	v_add_f32_e32 v208, v215, v208
	s_nop 1
	v_add_f32_dpp v208, v208, v208 quad_perm:[1,0,3,2] row_mask:0xf bank_mask:0xf
	s_nop 1
	v_add_f32_dpp v208, v208, v208 quad_perm:[2,3,0,1] row_mask:0xf bank_mask:0xf
	s_nop 1
	v_mov_b32_dpp v209, v208 row_half_mirror row_mask:0xf bank_mask:0xf
	v_add_f32_e32 v208, v208, v209
	v_fmamk_f32 v208, v208, 0x3c800000, v114
	v_rsq_f32_e32 v208, v208
	s_nop 0
	v_mul_f32_e32 v200, v208, v200
	v_mul_f32_e32 v201, v208, v201
	v_mul_f32_e32 v202, v208, v202
	v_mul_f32_e32 v203, v208, v203
	v_mul_f32_e32 v204, v208, v204
	v_mul_f32_e32 v205, v208, v205
	v_mul_f32_e32 v206, v208, v206
	v_mul_f32_e32 v207, v208, v207
	v_mul_f32_e32 v200, v106, v200
	v_mul_f32_e32 v201, v107, v201
	v_mul_f32_e32 v202, v108, v202
	v_mul_f32_e32 v203, v109, v203
	v_mul_f32_e32 v204, v110, v204
	v_mul_f32_e32 v205, v111, v205
	v_mul_f32_e32 v206, v112, v206
	v_mul_f32_e32 v207, v113, v207
	v_cvt_pk_bf16_f32 v128, v200, v201
	v_cvt_pk_bf16_f32 v129, v202, v203
	v_cvt_pk_bf16_f32 v130, v204, v205
	v_cvt_pk_bf16_f32 v131, v206, v207
	global_store_dwordx4 v186, v[128:131], s[12:13]
	s_add_u32 s14, s14, s17
	s_cmp_ge_u32 s14, 0x8000
	s_cbranch_scc1 .Lkn_st_end
	v_lshlrev_b32_e32 v200, 16, v132
	v_and_b32_e32 v201, 0xffff0000, v132
	v_lshlrev_b32_e32 v202, 16, v133
	v_and_b32_e32 v203, 0xffff0000, v133
	v_lshlrev_b32_e32 v204, 16, v134
	v_and_b32_e32 v205, 0xffff0000, v134
	v_lshlrev_b32_e32 v206, 16, v135
	v_and_b32_e32 v207, 0xffff0000, v135
	v_pk_mul_f32 v[208:209], v[200:201], v[200:201]
	v_pk_mul_f32 v[210:211], v[202:203], v[202:203]
	v_pk_mul_f32 v[212:213], v[204:205], v[204:205]
	v_pk_mul_f32 v[214:215], v[206:207], v[206:207]
	v_add_f32_e32 v208, v208, v209
	v_add_f32_e32 v208, v210, v208
	v_add_f32_e32 v208, v211, v208
	v_add_f32_e32 v208, v212, v208
	v_add_f32_e32 v208, v213, v208
	v_add_f32_e32 v208, v214, v208
	v_add_f32_e32 v208, v215, v208
	s_nop 1
	v_add_f32_dpp v208, v208, v208 quad_perm:[1,0,3,2] row_mask:0xf bank_mask:0xf
	s_nop 1
	v_add_f32_dpp v208, v208, v208 quad_perm:[2,3,0,1] row_mask:0xf bank_mask:0xf
	s_nop 1
	v_mov_b32_dpp v209, v208 row_half_mirror row_mask:0xf bank_mask:0xf
	v_add_f32_e32 v208, v208, v209
	v_fmamk_f32 v208, v208, 0x3c800000, v114
	v_rsq_f32_e32 v208, v208
	s_nop 0
	v_mul_f32_e32 v200, v208, v200
	v_mul_f32_e32 v201, v208, v201
	v_mul_f32_e32 v202, v208, v202
	v_mul_f32_e32 v203, v208, v203
	v_mul_f32_e32 v204, v208, v204
	v_mul_f32_e32 v205, v208, v205
	v_mul_f32_e32 v206, v208, v206
	v_mul_f32_e32 v207, v208, v207
	v_mul_f32_e32 v200, v106, v200
	v_mul_f32_e32 v201, v107, v201
	v_mul_f32_e32 v202, v108, v202
	v_mul_f32_e32 v203, v109, v203
	v_mul_f32_e32 v204, v110, v204
	v_mul_f32_e32 v205, v111, v205
	v_mul_f32_e32 v206, v112, v206
	v_mul_f32_e32 v207, v113, v207
	v_cvt_pk_bf16_f32 v132, v200, v201
	v_cvt_pk_bf16_f32 v133, v202, v203
	v_cvt_pk_bf16_f32 v134, v204, v205
	v_cvt_pk_bf16_f32 v135, v206, v207
	global_store_dwordx4 v187, v[132:135], s[12:13]
	s_add_u32 s14, s14, s17
	s_cmp_ge_u32 s14, 0x8000
	s_cbranch_scc1 .Lkn_st_end
	v_lshlrev_b32_e32 v200, 16, v136
	v_and_b32_e32 v201, 0xffff0000, v136
	v_lshlrev_b32_e32 v202, 16, v137
	v_and_b32_e32 v203, 0xffff0000, v137
	v_lshlrev_b32_e32 v204, 16, v138
	v_and_b32_e32 v205, 0xffff0000, v138
	v_lshlrev_b32_e32 v206, 16, v139
	v_and_b32_e32 v207, 0xffff0000, v139
	v_pk_mul_f32 v[208:209], v[200:201], v[200:201]
	v_pk_mul_f32 v[210:211], v[202:203], v[202:203]
	v_pk_mul_f32 v[212:213], v[204:205], v[204:205]
	v_pk_mul_f32 v[214:215], v[206:207], v[206:207]
	v_add_f32_e32 v208, v208, v209
	v_add_f32_e32 v208, v210, v208
	v_add_f32_e32 v208, v211, v208
	v_add_f32_e32 v208, v212, v208
	v_add_f32_e32 v208, v213, v208
	v_add_f32_e32 v208, v214, v208
	v_add_f32_e32 v208, v215, v208
	s_nop 1
	v_add_f32_dpp v208, v208, v208 quad_perm:[1,0,3,2] row_mask:0xf bank_mask:0xf
	s_nop 1
	v_add_f32_dpp v208, v208, v208 quad_perm:[2,3,0,1] row_mask:0xf bank_mask:0xf
	s_nop 1
	v_mov_b32_dpp v209, v208 row_half_mirror row_mask:0xf bank_mask:0xf
	v_add_f32_e32 v208, v208, v209
	v_fmamk_f32 v208, v208, 0x3c800000, v114
	v_rsq_f32_e32 v208, v208
	s_nop 0
	v_mul_f32_e32 v200, v208, v200
	v_mul_f32_e32 v201, v208, v201
	v_mul_f32_e32 v202, v208, v202
	v_mul_f32_e32 v203, v208, v203
	v_mul_f32_e32 v204, v208, v204
	v_mul_f32_e32 v205, v208, v205
	v_mul_f32_e32 v206, v208, v206
	v_mul_f32_e32 v207, v208, v207
	v_mul_f32_e32 v200, v106, v200
	v_mul_f32_e32 v201, v107, v201
	v_mul_f32_e32 v202, v108, v202
	v_mul_f32_e32 v203, v109, v203
	v_mul_f32_e32 v204, v110, v204
	v_mul_f32_e32 v205, v111, v205
	v_mul_f32_e32 v206, v112, v206
	v_mul_f32_e32 v207, v113, v207
	v_cvt_pk_bf16_f32 v136, v200, v201
	v_cvt_pk_bf16_f32 v137, v202, v203
	v_cvt_pk_bf16_f32 v138, v204, v205
	v_cvt_pk_bf16_f32 v139, v206, v207
	global_store_dwordx4 v188, v[136:139], s[12:13]
	s_add_u32 s14, s14, s17
	s_cmp_ge_u32 s14, 0x8000
	s_cbranch_scc1 .Lkn_st_end
	v_lshlrev_b32_e32 v200, 16, v140
	v_and_b32_e32 v201, 0xffff0000, v140
	v_lshlrev_b32_e32 v202, 16, v141
	v_and_b32_e32 v203, 0xffff0000, v141
	v_lshlrev_b32_e32 v204, 16, v142
	v_and_b32_e32 v205, 0xffff0000, v142
	v_lshlrev_b32_e32 v206, 16, v143
	v_and_b32_e32 v207, 0xffff0000, v143
	v_pk_mul_f32 v[208:209], v[200:201], v[200:201]
	v_pk_mul_f32 v[210:211], v[202:203], v[202:203]
	v_pk_mul_f32 v[212:213], v[204:205], v[204:205]
	v_pk_mul_f32 v[214:215], v[206:207], v[206:207]
	v_add_f32_e32 v208, v208, v209
	v_add_f32_e32 v208, v210, v208
	v_add_f32_e32 v208, v211, v208
	v_add_f32_e32 v208, v212, v208
	v_add_f32_e32 v208, v213, v208
	v_add_f32_e32 v208, v214, v208
	v_add_f32_e32 v208, v215, v208
	s_nop 1
	v_add_f32_dpp v208, v208, v208 quad_perm:[1,0,3,2] row_mask:0xf bank_mask:0xf
	s_nop 1
	v_add_f32_dpp v208, v208, v208 quad_perm:[2,3,0,1] row_mask:0xf bank_mask:0xf
	s_nop 1
	v_mov_b32_dpp v209, v208 row_half_mirror row_mask:0xf bank_mask:0xf
	v_add_f32_e32 v208, v208, v209
	v_fmamk_f32 v208, v208, 0x3c800000, v114
	v_rsq_f32_e32 v208, v208
	s_nop 0
	v_mul_f32_e32 v200, v208, v200
	v_mul_f32_e32 v201, v208, v201
	v_mul_f32_e32 v202, v208, v202
	v_mul_f32_e32 v203, v208, v203
	v_mul_f32_e32 v204, v208, v204
	v_mul_f32_e32 v205, v208, v205
	v_mul_f32_e32 v206, v208, v206
	v_mul_f32_e32 v207, v208, v207
	v_mul_f32_e32 v200, v106, v200
	v_mul_f32_e32 v201, v107, v201
	v_mul_f32_e32 v202, v108, v202
	v_mul_f32_e32 v203, v109, v203
	v_mul_f32_e32 v204, v110, v204
	v_mul_f32_e32 v205, v111, v205
	v_mul_f32_e32 v206, v112, v206
	v_mul_f32_e32 v207, v113, v207
	v_cvt_pk_bf16_f32 v140, v200, v201
	v_cvt_pk_bf16_f32 v141, v202, v203
	v_cvt_pk_bf16_f32 v142, v204, v205
	v_cvt_pk_bf16_f32 v143, v206, v207
	global_store_dwordx4 v189, v[140:143], s[12:13]
	s_add_u32 s14, s14, s17
	s_cmp_ge_u32 s14, 0x8000
	s_cbranch_scc1 .Lkn_st_end
	v_lshlrev_b32_e32 v200, 16, v144
	v_and_b32_e32 v201, 0xffff0000, v144
	v_lshlrev_b32_e32 v202, 16, v145
	v_and_b32_e32 v203, 0xffff0000, v145
	v_lshlrev_b32_e32 v204, 16, v146
	v_and_b32_e32 v205, 0xffff0000, v146
	v_lshlrev_b32_e32 v206, 16, v147
	v_and_b32_e32 v207, 0xffff0000, v147
	v_pk_mul_f32 v[208:209], v[200:201], v[200:201]
	v_pk_mul_f32 v[210:211], v[202:203], v[202:203]
	v_pk_mul_f32 v[212:213], v[204:205], v[204:205]
	v_pk_mul_f32 v[214:215], v[206:207], v[206:207]
	v_add_f32_e32 v208, v208, v209
	v_add_f32_e32 v208, v210, v208
	v_add_f32_e32 v208, v211, v208
	v_add_f32_e32 v208, v212, v208
	v_add_f32_e32 v208, v213, v208
	v_add_f32_e32 v208, v214, v208
	v_add_f32_e32 v208, v215, v208
	s_nop 1
	v_add_f32_dpp v208, v208, v208 quad_perm:[1,0,3,2] row_mask:0xf bank_mask:0xf
	s_nop 1
	v_add_f32_dpp v208, v208, v208 quad_perm:[2,3,0,1] row_mask:0xf bank_mask:0xf
	s_nop 1
	v_mov_b32_dpp v209, v208 row_half_mirror row_mask:0xf bank_mask:0xf
	v_add_f32_e32 v208, v208, v209
	v_fmamk_f32 v208, v208, 0x3c800000, v114
	v_rsq_f32_e32 v208, v208
	s_nop 0
	v_mul_f32_e32 v200, v208, v200
	v_mul_f32_e32 v201, v208, v201
	v_mul_f32_e32 v202, v208, v202
	v_mul_f32_e32 v203, v208, v203
	v_mul_f32_e32 v204, v208, v204
	v_mul_f32_e32 v205, v208, v205
	v_mul_f32_e32 v206, v208, v206
	v_mul_f32_e32 v207, v208, v207
	v_mul_f32_e32 v200, v106, v200
	v_mul_f32_e32 v201, v107, v201
	v_mul_f32_e32 v202, v108, v202
	v_mul_f32_e32 v203, v109, v203
	v_mul_f32_e32 v204, v110, v204
	v_mul_f32_e32 v205, v111, v205
	v_mul_f32_e32 v206, v112, v206
	v_mul_f32_e32 v207, v113, v207
	v_cvt_pk_bf16_f32 v144, v200, v201
	v_cvt_pk_bf16_f32 v145, v202, v203
	v_cvt_pk_bf16_f32 v146, v204, v205
	v_cvt_pk_bf16_f32 v147, v206, v207
	global_store_dwordx4 v190, v[144:147], s[12:13]
	s_add_u32 s14, s14, s17
	s_cmp_ge_u32 s14, 0x8000
	s_cbranch_scc1 .Lkn_st_end
	v_lshlrev_b32_e32 v200, 16, v148
	v_and_b32_e32 v201, 0xffff0000, v148
	v_lshlrev_b32_e32 v202, 16, v149
	v_and_b32_e32 v203, 0xffff0000, v149
	v_lshlrev_b32_e32 v204, 16, v150
	v_and_b32_e32 v205, 0xffff0000, v150
	v_lshlrev_b32_e32 v206, 16, v151
	v_and_b32_e32 v207, 0xffff0000, v151
	v_pk_mul_f32 v[208:209], v[200:201], v[200:201]
	v_pk_mul_f32 v[210:211], v[202:203], v[202:203]
	v_pk_mul_f32 v[212:213], v[204:205], v[204:205]
	v_pk_mul_f32 v[214:215], v[206:207], v[206:207]
	v_add_f32_e32 v208, v208, v209
	v_add_f32_e32 v208, v210, v208
	v_add_f32_e32 v208, v211, v208
	v_add_f32_e32 v208, v212, v208
	v_add_f32_e32 v208, v213, v208
	v_add_f32_e32 v208, v214, v208
	v_add_f32_e32 v208, v215, v208
	s_nop 1
	v_add_f32_dpp v208, v208, v208 quad_perm:[1,0,3,2] row_mask:0xf bank_mask:0xf
	s_nop 1
	v_add_f32_dpp v208, v208, v208 quad_perm:[2,3,0,1] row_mask:0xf bank_mask:0xf
	s_nop 1
	v_mov_b32_dpp v209, v208 row_half_mirror row_mask:0xf bank_mask:0xf
	v_add_f32_e32 v208, v208, v209
	v_fmamk_f32 v208, v208, 0x3c800000, v114
	v_rsq_f32_e32 v208, v208
	s_nop 0
	v_mul_f32_e32 v200, v208, v200
	v_mul_f32_e32 v201, v208, v201
	v_mul_f32_e32 v202, v208, v202
	v_mul_f32_e32 v203, v208, v203
	v_mul_f32_e32 v204, v208, v204
	v_mul_f32_e32 v205, v208, v205
	v_mul_f32_e32 v206, v208, v206
	v_mul_f32_e32 v207, v208, v207
	v_mul_f32_e32 v200, v106, v200
	v_mul_f32_e32 v201, v107, v201
	v_mul_f32_e32 v202, v108, v202
	v_mul_f32_e32 v203, v109, v203
	v_mul_f32_e32 v204, v110, v204
	v_mul_f32_e32 v205, v111, v205
	v_mul_f32_e32 v206, v112, v206
	v_mul_f32_e32 v207, v113, v207
	v_cvt_pk_bf16_f32 v148, v200, v201
	v_cvt_pk_bf16_f32 v149, v202, v203
	v_cvt_pk_bf16_f32 v150, v204, v205
	v_cvt_pk_bf16_f32 v151, v206, v207
	global_store_dwordx4 v191, v[148:151], s[12:13]
	s_add_u32 s14, s14, s17
